# EpiAct GEMM epilogue: row-statistics loads issued one output row ahead with counted vmcnt (global stores)
# speedup vs baseline: 1.0482x; 1.0063x over previous
.LBB0_600:
	v_lshl_add_u32 v162, s71, 8, v202
	v_lshlrev_b32_e32 v238, 6, v162
	v_add_u32_e32 v239, 0x2000, v238
	v_ashrrev_i32_e32 v163, 31, v162
	v_lshlrev_b64 v[164:165], 6, v[162:163]
	v_lshl_add_u64 v[172:173], s[40:41], 0, v[164:165]
	flat_load_dwordx4 v[164:167], v[172:173]
	flat_load_dwordx4 v[168:171], v[172:173] offset:16
	flat_load_dwordx4 v[206:209], v[172:173] offset:32
	flat_load_dwordx4 v[210:213], v[172:173] offset:48
	global_load_dwordx4 v[214:217], v238, s[40:41] offset:1024
	global_load_dwordx4 v[218:221], v238, s[40:41] offset:1040
	global_load_dwordx4 v[222:225], v238, s[40:41] offset:1056
	global_load_dwordx4 v[226:229], v238, s[40:41] offset:1072
	s_cmp_ge_i32 s22, s63
	s_cselect_b64 s[22:23], -1, 0
	s_xor_b64 s[24:25], s[34:35], -1
	s_or_b64 s[22:23], s[24:25], s[22:23]
	s_mov_b64 s[4:5], -1
	s_and_b64 vcc, exec, s[22:23]
	s_waitcnt vmcnt(4) lgkmcnt(0)
	v_mov_b32_e32 v172, v165
	v_mov_b32_e32 v173, v166
	v_mov_b32_e32 v165, v167
	v_mov_b32_e32 v166, v169
	v_mov_b32_e32 v167, v170
	v_mov_b32_e32 v169, v171
	v_pk_add_f32 v[164:165], v[172:173], v[164:165]
	v_pk_add_f32 v[166:167], v[166:167], v[168:169]
	v_pk_add_f32 v[164:165], v[164:165], v[164:165] op_sel:[0,1] op_sel_hi:[1,0]
	v_pk_add_f32 v[166:167], v[166:167], v[166:167] op_sel:[0,1] op_sel_hi:[1,0]
	v_add_f32_e32 v168, v206, v207
	v_add_f32_e32 v170, v208, v209
	v_mov_b32_e32 v165, v210
	v_mov_b32_e32 v167, v211
	v_mov_b32_e32 v169, v212
	v_mov_b32_e32 v171, v213
	v_pk_add_f32 v[164:165], v[164:165], v[166:167]
	v_pk_add_f32 v[166:167], v[168:169], v[170:171]
	s_nop 0
	v_pk_add_f32 v[164:165], v[164:165], v[166:167]
	s_nop 0
	v_add_f32_e32 v164, v164, v165
	v_fmamk_f32 v164, v164, 0x3a800000, v183
	v_rsq_f32_e32 v164, v164
	s_nop 0
	v_mul_f32_e32 v164, s62, v164
	v_pk_fma_f32 v[142:143], v[142:143], v[164:165], v[38:39] op_sel_hi:[1,0,1]
	v_pk_fma_f32 v[140:141], v[140:141], v[164:165], v[36:37] op_sel_hi:[1,0,1]
	v_pk_fma_f32 v[138:139], v[138:139], v[164:165], v[34:35] op_sel_hi:[1,0,1]
	v_pk_fma_f32 v[136:137], v[136:137], v[164:165], v[32:33] op_sel_hi:[1,0,1]
	s_cbranch_vccz .LBB0_604
	s_andn2_b64 vcc, exec, s[30:31]
	v_mov_b32_e32 v171, v139
	v_mov_b32_e32 v170, v138
	v_mov_b32_e32 v173, v137
	v_mov_b32_e32 v172, v136
	v_mov_b32_e32 v167, v143
	v_mov_b32_e32 v166, v142
	v_mov_b32_e32 v169, v141
	v_mov_b32_e32 v168, v140
	s_cbranch_vccnz .LBB0_603
	v_max_f32_e32 v165, v140, v140
	v_max_f32_e32 v166, 0, v165
	v_max_f32_e32 v165, v136, v136
	v_max_f32_e32 v170, 0, v165
	v_max_f32_e32 v165, v141, v141
	v_max_f32_e32 v167, 0, v165
	v_max_f32_e32 v165, v137, v137
	v_max_f32_e32 v171, 0, v165
	v_max_f32_e32 v165, v142, v142
	v_max_f32_e32 v172, 0, v165
	v_max_f32_e32 v165, v138, v138
	v_max_f32_e32 v184, 0, v165
	v_max_f32_e32 v165, v143, v143
	v_max_f32_e32 v173, 0, v165
	v_max_f32_e32 v165, v139, v139
	v_max_f32_e32 v185, 0, v165
	v_pk_mul_f32 v[168:169], v[166:167], v[166:167]
	v_pk_mul_f32 v[166:167], v[172:173], v[172:173]
	v_pk_mul_f32 v[172:173], v[170:171], v[170:171]
	v_pk_mul_f32 v[170:171], v[184:185], v[184:185]

.LBB0_606:
	v_mad_u64_u32 v[136:137], s[4:5], v162, s60, 0
	v_mov_b32_e32 v138, v137
	v_mad_u64_u32 v[138:139], s[4:5], v163, s60, v[138:139]
	v_mov_b32_e32 v137, v138
	v_lshl_add_u64 v[136:137], v[136:137], 1, s[36:37]
	v_lshl_add_u64 v[136:137], v[160:161], 1, v[136:137]
	v_cvt_pk_bf16_f32 v138, v168, v169
	v_cvt_pk_bf16_f32 v139, v166, v167
	v_cvt_pk_bf16_f32 v140, v172, v173
	v_cvt_pk_bf16_f32 v141, v170, v171
	global_store_dwordx4 v[136:137], v[138:141], off
	v_mov_b32_e32 v165, v164
	v_pk_fma_f32 v[132:133], v[132:133], v[164:165], v[28:29]
	v_mov_b32_e32 v138, v164
	v_mov_b32_e32 v139, v164
	v_pk_fma_f32 v[134:135], v[134:135], v[138:139], v[30:31]
	v_pk_fma_f32 v[130:131], v[130:131], v[138:139], v[26:27]
	v_cndmask_b32_e64 v138, 0, 1, s[22:23]
	v_pk_fma_f32 v[128:129], v[128:129], v[164:165], v[24:25]
	v_cmp_ne_u32_e64 s[4:5], 1, v138
	s_andn2_b64 vcc, exec, s[22:23]
	s_mov_b64 s[22:23], -1
	s_cbranch_vccnz .LBB0_610
	s_andn2_b64 vcc, exec, s[30:31]
	v_mov_b32_e32 v143, v131
	v_mov_b32_e32 v142, v130
	v_mov_b32_e32 v165, v129
	v_mov_b32_e32 v164, v128
	v_mov_b32_e32 v139, v135
	v_mov_b32_e32 v138, v134
	v_mov_b32_e32 v141, v133
	v_mov_b32_e32 v140, v132
	s_cbranch_vccnz .LBB0_609
	v_max_f32_e32 v140, v129, v129
	v_max_f32_e32 v143, 0, v140
	v_max_f32_e32 v140, v134, v134
	v_max_f32_e32 v164, 0, v140
	v_max_f32_e32 v140, v130, v130
	v_max_f32_e32 v139, v128, v128
	v_max_f32_e32 v166, 0, v140
	v_max_f32_e32 v140, v135, v135
	v_max_f32_e32 v138, v132, v132
	v_max_f32_e32 v142, 0, v139
	v_max_f32_e32 v139, v133, v133
	v_max_f32_e32 v165, 0, v140
	v_max_f32_e32 v140, v131, v131
	v_max_f32_e32 v138, 0, v138
	v_max_f32_e32 v139, 0, v139
	v_max_f32_e32 v167, 0, v140
	v_pk_mul_f32 v[140:141], v[138:139], v[138:139]
	v_pk_mul_f32 v[138:139], v[164:165], v[164:165]
	v_pk_mul_f32 v[164:165], v[142:143], v[142:143]
	v_pk_mul_f32 v[142:143], v[166:167], v[166:167]

.LBB0_612:
	v_cvt_pk_bf16_f32 v128, v140, v141
	v_cvt_pk_bf16_f32 v129, v138, v139
	v_cvt_pk_bf16_f32 v130, v164, v165
	v_cvt_pk_bf16_f32 v131, v142, v143
	global_store_dwordx4 v[136:137], v[128:131], off offset:256
	s_mov_b64 s[22:23], -1
	s_and_b64 vcc, exec, s[4:5]
	v_or_b32_e32 v128, 16, v162
	v_ashrrev_i32_e32 v129, 31, v128
	v_lshlrev_b64 v[130:131], 6, v[128:129]
	v_lshl_add_u64 v[142:143], s[40:41], 0, v[130:131]
	global_load_dwordx4 v[230:233], v238, s[40:41] offset:2048
	global_load_dwordx4 v[234:237], v238, s[40:41] offset:2064
	global_load_dwordx4 v[206:209], v238, s[40:41] offset:2080
	global_load_dwordx4 v[210:213], v238, s[40:41] offset:2096
	s_waitcnt vmcnt(6) lgkmcnt(0)
	v_mov_b32_e32 v130, v214
	v_mov_b32_e32 v131, v215
	v_mov_b32_e32 v132, v216
	v_mov_b32_e32 v133, v217
	v_mov_b32_e32 v134, v218
	v_mov_b32_e32 v135, v219
	v_mov_b32_e32 v136, v220
	v_mov_b32_e32 v137, v221
	v_mov_b32_e32 v138, v222
	v_mov_b32_e32 v139, v223
	v_mov_b32_e32 v140, v224
	v_mov_b32_e32 v141, v225
	v_mov_b32_e32 v164, v226
	v_mov_b32_e32 v165, v227
	v_mov_b32_e32 v166, v228
	v_mov_b32_e32 v167, v229
	v_mov_b32_e32 v142, v131
	v_mov_b32_e32 v143, v132
	v_mov_b32_e32 v131, v133
	v_mov_b32_e32 v132, v135
	v_mov_b32_e32 v133, v136
	v_mov_b32_e32 v135, v137
	v_pk_add_f32 v[130:131], v[142:143], v[130:131]
	v_pk_add_f32 v[132:133], v[132:133], v[134:135]
	v_pk_add_f32 v[130:131], v[130:131], v[130:131] op_sel:[0,1] op_sel_hi:[1,0]
	v_pk_add_f32 v[132:133], v[132:133], v[132:133] op_sel:[0,1] op_sel_hi:[1,0]
	v_add_f32_e32 v134, v138, v139
	v_add_f32_e32 v136, v140, v141
	v_mov_b32_e32 v131, v164
	v_mov_b32_e32 v133, v165
	v_mov_b32_e32 v135, v166
	v_mov_b32_e32 v137, v167
	v_pk_add_f32 v[130:131], v[130:131], v[132:133]
	v_pk_add_f32 v[132:133], v[134:135], v[136:137]
	s_nop 0
	v_pk_add_f32 v[130:131], v[130:131], v[132:133]
	s_nop 0
	v_add_f32_e32 v130, v130, v131
	v_fmamk_f32 v130, v130, 0x3a800000, v183
	v_rsq_f32_e32 v130, v130
	s_nop 0
	v_mul_f32_e32 v130, s62, v130
	v_pk_fma_f32 v[126:127], v[126:127], v[130:131], v[38:39] op_sel_hi:[1,0,1]
	v_pk_fma_f32 v[124:125], v[124:125], v[130:131], v[36:37] op_sel_hi:[1,0,1]
	v_pk_fma_f32 v[122:123], v[122:123], v[130:131], v[34:35] op_sel_hi:[1,0,1]
	v_pk_fma_f32 v[120:121], v[120:121], v[130:131], v[32:33] op_sel_hi:[1,0,1]
	s_cbranch_vccnz .LBB0_616
	s_andn2_b64 vcc, exec, s[30:31]
	v_mov_b32_e32 v137, v123
	v_mov_b32_e32 v136, v122
	v_mov_b32_e32 v139, v121
	v_mov_b32_e32 v138, v120
	v_mov_b32_e32 v133, v127
	v_mov_b32_e32 v132, v126
	v_mov_b32_e32 v135, v125
	v_mov_b32_e32 v134, v124
	s_cbranch_vccnz .LBB0_615
	v_max_f32_e32 v131, v124, v124
	v_max_f32_e32 v132, 0, v131
	v_max_f32_e32 v131, v120, v120
	v_max_f32_e32 v136, 0, v131
	v_max_f32_e32 v131, v125, v125
	v_max_f32_e32 v133, 0, v131
	v_max_f32_e32 v131, v121, v121
	v_max_f32_e32 v137, 0, v131
	v_max_f32_e32 v131, v126, v126
	v_max_f32_e32 v138, 0, v131
	v_max_f32_e32 v131, v122, v122
	v_max_f32_e32 v140, 0, v131
	v_max_f32_e32 v131, v127, v127
	v_max_f32_e32 v139, 0, v131
	v_max_f32_e32 v131, v123, v123
	v_max_f32_e32 v141, 0, v131
	v_pk_mul_f32 v[134:135], v[132:133], v[132:133]
	v_pk_mul_f32 v[132:133], v[138:139], v[138:139]
	v_pk_mul_f32 v[138:139], v[136:137], v[136:137]
	v_pk_mul_f32 v[136:137], v[140:141], v[140:141]

.LBB0_618:
	v_mad_u64_u32 v[120:121], s[22:23], v128, s60, 0
	v_mov_b32_e32 v122, v121
	v_mad_u64_u32 v[122:123], s[22:23], v129, s60, v[122:123]
	v_mov_b32_e32 v121, v122
	v_lshl_add_u64 v[120:121], v[120:121], 1, s[36:37]
	v_lshl_add_u64 v[120:121], v[160:161], 1, v[120:121]
	v_cvt_pk_bf16_f32 v122, v134, v135
	v_cvt_pk_bf16_f32 v123, v132, v133
	v_cvt_pk_bf16_f32 v124, v138, v139
	v_cvt_pk_bf16_f32 v125, v136, v137
	v_mov_b32_e32 v131, v130
	global_store_dwordx4 v[120:121], v[122:125], off
	v_pk_fma_f32 v[116:117], v[116:117], v[130:131], v[28:29]
	v_pk_fma_f32 v[112:113], v[112:113], v[130:131], v[24:25]
	v_mov_b32_e32 v122, v130
	v_mov_b32_e32 v123, v130
	v_pk_fma_f32 v[118:119], v[118:119], v[122:123], v[30:31]
	v_pk_fma_f32 v[114:115], v[114:115], v[122:123], v[26:27]
	s_and_b64 vcc, exec, s[4:5]
	s_mov_b64 s[22:23], -1
	s_cbranch_vccnz .LBB0_622
	s_andn2_b64 vcc, exec, s[30:31]
	v_mov_b32_e32 v127, v115
	v_mov_b32_e32 v126, v114
	v_mov_b32_e32 v129, v113
	v_mov_b32_e32 v128, v112
	v_mov_b32_e32 v123, v119
	v_mov_b32_e32 v122, v118
	v_mov_b32_e32 v125, v117
	v_mov_b32_e32 v124, v116
	s_cbranch_vccnz .LBB0_621
	v_max_f32_e32 v124, v113, v113
	v_max_f32_e32 v127, 0, v124
	v_max_f32_e32 v124, v118, v118
	v_max_f32_e32 v128, 0, v124
	v_max_f32_e32 v124, v114, v114
	v_max_f32_e32 v123, v112, v112
	v_max_f32_e32 v130, 0, v124
	v_max_f32_e32 v124, v119, v119
	v_max_f32_e32 v122, v116, v116
	v_max_f32_e32 v126, 0, v123
	v_max_f32_e32 v123, v117, v117
	v_max_f32_e32 v129, 0, v124
	v_max_f32_e32 v124, v115, v115
	v_max_f32_e32 v122, 0, v122
	v_max_f32_e32 v123, 0, v123
	v_max_f32_e32 v131, 0, v124
	v_pk_mul_f32 v[124:125], v[122:123], v[122:123]
	v_pk_mul_f32 v[122:123], v[128:129], v[128:129]
	v_pk_mul_f32 v[128:129], v[126:127], v[126:127]
	v_pk_mul_f32 v[126:127], v[130:131], v[130:131]

.LBB0_624:
	v_cvt_pk_bf16_f32 v112, v124, v125
	v_cvt_pk_bf16_f32 v113, v122, v123
	v_cvt_pk_bf16_f32 v114, v128, v129
	v_cvt_pk_bf16_f32 v115, v126, v127
	global_store_dwordx4 v[120:121], v[112:115], off offset:256
	s_mov_b64 s[22:23], -1
	s_and_b64 vcc, exec, s[4:5]
	v_or_b32_e32 v112, 32, v162
	v_ashrrev_i32_e32 v113, 31, v112
	v_lshlrev_b64 v[114:115], 6, v[112:113]
	v_lshl_add_u64 v[126:127], s[40:41], 0, v[114:115]
	global_load_dwordx4 v[214:217], v238, s[40:41] offset:3072
	global_load_dwordx4 v[218:221], v238, s[40:41] offset:3088
	global_load_dwordx4 v[222:225], v238, s[40:41] offset:3104
	global_load_dwordx4 v[226:229], v238, s[40:41] offset:3120
	s_waitcnt vmcnt(6) lgkmcnt(0)
	v_mov_b32_e32 v114, v230
	v_mov_b32_e32 v115, v231
	v_mov_b32_e32 v116, v232
	v_mov_b32_e32 v117, v233
	v_mov_b32_e32 v118, v234
	v_mov_b32_e32 v119, v235
	v_mov_b32_e32 v120, v236
	v_mov_b32_e32 v121, v237
	v_mov_b32_e32 v122, v206
	v_mov_b32_e32 v123, v207
	v_mov_b32_e32 v124, v208
	v_mov_b32_e32 v125, v209
	v_mov_b32_e32 v126, v210
	v_mov_b32_e32 v127, v211
	v_mov_b32_e32 v128, v212
	v_mov_b32_e32 v129, v213
	v_mov_b32_e32 v130, v115
	v_mov_b32_e32 v131, v116
	v_mov_b32_e32 v115, v117
	v_mov_b32_e32 v116, v119
	v_mov_b32_e32 v117, v120
	v_mov_b32_e32 v119, v121
	v_pk_add_f32 v[114:115], v[130:131], v[114:115]
	v_pk_add_f32 v[116:117], v[116:117], v[118:119]
	v_pk_add_f32 v[114:115], v[114:115], v[114:115] op_sel:[0,1] op_sel_hi:[1,0]
	v_pk_add_f32 v[116:117], v[116:117], v[116:117] op_sel:[0,1] op_sel_hi:[1,0]
	v_add_f32_e32 v118, v122, v123
	v_add_f32_e32 v120, v124, v125
	v_mov_b32_e32 v115, v126
	v_mov_b32_e32 v117, v127
	v_mov_b32_e32 v119, v128
	v_mov_b32_e32 v121, v129
	v_pk_add_f32 v[114:115], v[114:115], v[116:117]
	v_pk_add_f32 v[116:117], v[118:119], v[120:121]
	s_nop 0
	v_pk_add_f32 v[114:115], v[114:115], v[116:117]
	s_nop 0
	v_add_f32_e32 v114, v114, v115
	v_fmamk_f32 v114, v114, 0x3a800000, v183
	v_rsq_f32_e32 v114, v114
	s_nop 0
	v_mul_f32_e32 v114, s62, v114
	v_pk_fma_f32 v[110:111], v[110:111], v[114:115], v[38:39] op_sel_hi:[1,0,1]
	v_pk_fma_f32 v[108:109], v[108:109], v[114:115], v[36:37] op_sel_hi:[1,0,1]
	v_pk_fma_f32 v[106:107], v[106:107], v[114:115], v[34:35] op_sel_hi:[1,0,1]
	v_pk_fma_f32 v[104:105], v[104:105], v[114:115], v[32:33] op_sel_hi:[1,0,1]
	s_cbranch_vccnz .LBB0_628
	s_andn2_b64 vcc, exec, s[30:31]
	v_mov_b32_e32 v121, v107
	v_mov_b32_e32 v120, v106
	v_mov_b32_e32 v123, v105
	v_mov_b32_e32 v122, v104
	v_mov_b32_e32 v117, v111
	v_mov_b32_e32 v116, v110
	v_mov_b32_e32 v119, v109
	v_mov_b32_e32 v118, v108
	s_cbranch_vccnz .LBB0_627
	v_max_f32_e32 v115, v108, v108
	v_max_f32_e32 v116, 0, v115
	v_max_f32_e32 v115, v104, v104
	v_max_f32_e32 v120, 0, v115
	v_max_f32_e32 v115, v109, v109
	v_max_f32_e32 v117, 0, v115
	v_max_f32_e32 v115, v105, v105
	v_max_f32_e32 v121, 0, v115
	v_max_f32_e32 v115, v110, v110
	v_max_f32_e32 v122, 0, v115
	v_max_f32_e32 v115, v106, v106
	v_max_f32_e32 v124, 0, v115
	v_max_f32_e32 v115, v111, v111
	v_max_f32_e32 v123, 0, v115
	v_max_f32_e32 v115, v107, v107
	v_max_f32_e32 v125, 0, v115
	v_pk_mul_f32 v[118:119], v[116:117], v[116:117]
	v_pk_mul_f32 v[116:117], v[122:123], v[122:123]
	v_pk_mul_f32 v[122:123], v[120:121], v[120:121]
	v_pk_mul_f32 v[120:121], v[124:125], v[124:125]

.LBB0_630:
	v_mad_u64_u32 v[104:105], s[22:23], v112, s60, 0
	v_mov_b32_e32 v106, v105
	v_mad_u64_u32 v[106:107], s[22:23], v113, s60, v[106:107]
	v_mov_b32_e32 v105, v106
	v_lshl_add_u64 v[104:105], v[104:105], 1, s[36:37]
	v_lshl_add_u64 v[104:105], v[160:161], 1, v[104:105]
	v_cvt_pk_bf16_f32 v106, v118, v119
	v_cvt_pk_bf16_f32 v107, v116, v117
	v_cvt_pk_bf16_f32 v108, v122, v123
	v_cvt_pk_bf16_f32 v109, v120, v121
	v_mov_b32_e32 v115, v114
	global_store_dwordx4 v[104:105], v[106:109], off
	v_pk_fma_f32 v[100:101], v[100:101], v[114:115], v[28:29]
	v_pk_fma_f32 v[96:97], v[96:97], v[114:115], v[24:25]
	v_mov_b32_e32 v106, v114
	v_mov_b32_e32 v107, v114
	v_pk_fma_f32 v[102:103], v[102:103], v[106:107], v[30:31]
	v_pk_fma_f32 v[98:99], v[98:99], v[106:107], v[26:27]
	s_and_b64 vcc, exec, s[4:5]
	s_mov_b64 s[22:23], -1
	s_cbranch_vccnz .LBB0_634
	s_andn2_b64 vcc, exec, s[30:31]
	v_mov_b32_e32 v111, v99
	v_mov_b32_e32 v110, v98
	v_mov_b32_e32 v113, v97
	v_mov_b32_e32 v112, v96
	v_mov_b32_e32 v107, v103
	v_mov_b32_e32 v106, v102
	v_mov_b32_e32 v109, v101
	v_mov_b32_e32 v108, v100
	s_cbranch_vccnz .LBB0_633
	v_max_f32_e32 v108, v97, v97
	v_max_f32_e32 v111, 0, v108
	v_max_f32_e32 v108, v102, v102
	v_max_f32_e32 v112, 0, v108
	v_max_f32_e32 v108, v98, v98
	v_max_f32_e32 v107, v96, v96
	v_max_f32_e32 v114, 0, v108
	v_max_f32_e32 v108, v103, v103
	v_max_f32_e32 v106, v100, v100
	v_max_f32_e32 v110, 0, v107
	v_max_f32_e32 v107, v101, v101
	v_max_f32_e32 v113, 0, v108
	v_max_f32_e32 v108, v99, v99
	v_max_f32_e32 v106, 0, v106
	v_max_f32_e32 v107, 0, v107
	v_max_f32_e32 v115, 0, v108
	v_pk_mul_f32 v[108:109], v[106:107], v[106:107]
	v_pk_mul_f32 v[106:107], v[112:113], v[112:113]
	v_pk_mul_f32 v[112:113], v[110:111], v[110:111]
	v_pk_mul_f32 v[110:111], v[114:115], v[114:115]

.LBB0_636:
	v_cvt_pk_bf16_f32 v96, v108, v109
	v_cvt_pk_bf16_f32 v97, v106, v107
	v_cvt_pk_bf16_f32 v98, v112, v113
	v_cvt_pk_bf16_f32 v99, v110, v111
	global_store_dwordx4 v[104:105], v[96:99], off offset:256
	s_mov_b64 s[22:23], -1
	s_and_b64 vcc, exec, s[4:5]
	v_or_b32_e32 v96, 48, v162
	v_ashrrev_i32_e32 v97, 31, v96
	v_lshlrev_b64 v[98:99], 6, v[96:97]
	v_lshl_add_u64 v[110:111], s[40:41], 0, v[98:99]
	global_load_dwordx4 v[230:233], v239, s[40:41]
	global_load_dwordx4 v[234:237], v239, s[40:41] offset:16
	global_load_dwordx4 v[206:209], v239, s[40:41] offset:32
	global_load_dwordx4 v[210:213], v239, s[40:41] offset:48
	s_waitcnt vmcnt(6) lgkmcnt(0)
	v_mov_b32_e32 v98, v214
	v_mov_b32_e32 v99, v215
	v_mov_b32_e32 v100, v216
	v_mov_b32_e32 v101, v217
	v_mov_b32_e32 v102, v218
	v_mov_b32_e32 v103, v219
	v_mov_b32_e32 v104, v220
	v_mov_b32_e32 v105, v221
	v_mov_b32_e32 v106, v222
	v_mov_b32_e32 v107, v223
	v_mov_b32_e32 v108, v224
	v_mov_b32_e32 v109, v225
	v_mov_b32_e32 v110, v226
	v_mov_b32_e32 v111, v227
	v_mov_b32_e32 v112, v228
	v_mov_b32_e32 v113, v229
	v_mov_b32_e32 v114, v99
	v_mov_b32_e32 v115, v100
	v_mov_b32_e32 v99, v101
	v_mov_b32_e32 v100, v103
	v_mov_b32_e32 v101, v104
	v_mov_b32_e32 v103, v105
	v_pk_add_f32 v[98:99], v[114:115], v[98:99]
	v_pk_add_f32 v[100:101], v[100:101], v[102:103]
	v_pk_add_f32 v[98:99], v[98:99], v[98:99] op_sel:[0,1] op_sel_hi:[1,0]
	v_pk_add_f32 v[100:101], v[100:101], v[100:101] op_sel:[0,1] op_sel_hi:[1,0]
	v_add_f32_e32 v102, v106, v107
	v_add_f32_e32 v104, v108, v109
	v_mov_b32_e32 v99, v110
	v_mov_b32_e32 v101, v111
	v_mov_b32_e32 v103, v112
	v_mov_b32_e32 v105, v113
	v_pk_add_f32 v[98:99], v[98:99], v[100:101]
	v_pk_add_f32 v[100:101], v[102:103], v[104:105]
	s_nop 0
	v_pk_add_f32 v[98:99], v[98:99], v[100:101]
	s_nop 0
	v_add_f32_e32 v98, v98, v99
	v_fmamk_f32 v98, v98, 0x3a800000, v183
	v_rsq_f32_e32 v98, v98
	s_nop 0
	v_mul_f32_e32 v98, s62, v98
	v_pk_fma_f32 v[94:95], v[94:95], v[98:99], v[38:39] op_sel_hi:[1,0,1]
	v_pk_fma_f32 v[92:93], v[92:93], v[98:99], v[36:37] op_sel_hi:[1,0,1]
	v_pk_fma_f32 v[90:91], v[90:91], v[98:99], v[34:35] op_sel_hi:[1,0,1]
	v_pk_fma_f32 v[88:89], v[88:89], v[98:99], v[32:33] op_sel_hi:[1,0,1]
	s_cbranch_vccnz .LBB0_640
	s_andn2_b64 vcc, exec, s[30:31]
	v_mov_b32_e32 v105, v91
	v_mov_b32_e32 v104, v90
	v_mov_b32_e32 v107, v89
	v_mov_b32_e32 v106, v88
	v_mov_b32_e32 v101, v95
	v_mov_b32_e32 v100, v94
	v_mov_b32_e32 v103, v93
	v_mov_b32_e32 v102, v92
	s_cbranch_vccnz .LBB0_639
	v_max_f32_e32 v99, v92, v92
	v_max_f32_e32 v100, 0, v99
	v_max_f32_e32 v99, v88, v88
	v_max_f32_e32 v104, 0, v99
	v_max_f32_e32 v99, v93, v93
	v_max_f32_e32 v101, 0, v99
	v_max_f32_e32 v99, v89, v89
	v_max_f32_e32 v105, 0, v99
	v_max_f32_e32 v99, v94, v94
	v_max_f32_e32 v106, 0, v99
	v_max_f32_e32 v99, v90, v90
	v_max_f32_e32 v108, 0, v99
	v_max_f32_e32 v99, v95, v95
	v_max_f32_e32 v107, 0, v99
	v_max_f32_e32 v99, v91, v91
	v_max_f32_e32 v109, 0, v99
	v_pk_mul_f32 v[102:103], v[100:101], v[100:101]
	v_pk_mul_f32 v[100:101], v[106:107], v[106:107]
	v_pk_mul_f32 v[106:107], v[104:105], v[104:105]
	v_pk_mul_f32 v[104:105], v[108:109], v[108:109]

.LBB0_642:
	v_mad_u64_u32 v[88:89], s[22:23], v96, s60, 0
	v_mov_b32_e32 v90, v89
	v_mad_u64_u32 v[90:91], s[22:23], v97, s60, v[90:91]
	v_mov_b32_e32 v89, v90
	v_lshl_add_u64 v[88:89], v[88:89], 1, s[36:37]
	v_lshl_add_u64 v[88:89], v[160:161], 1, v[88:89]
	v_cvt_pk_bf16_f32 v90, v102, v103
	v_cvt_pk_bf16_f32 v91, v100, v101
	v_cvt_pk_bf16_f32 v92, v106, v107
	v_cvt_pk_bf16_f32 v93, v104, v105
	v_mov_b32_e32 v99, v98
	global_store_dwordx4 v[88:89], v[90:93], off
	v_pk_fma_f32 v[84:85], v[84:85], v[98:99], v[28:29]
	v_pk_fma_f32 v[80:81], v[80:81], v[98:99], v[24:25]
	v_mov_b32_e32 v90, v98
	v_mov_b32_e32 v91, v98
	v_pk_fma_f32 v[86:87], v[86:87], v[90:91], v[30:31]
	v_pk_fma_f32 v[82:83], v[82:83], v[90:91], v[26:27]
	s_and_b64 vcc, exec, s[4:5]
	s_mov_b64 s[22:23], -1
	s_cbranch_vccnz .LBB0_646
	s_andn2_b64 vcc, exec, s[30:31]
	v_mov_b32_e32 v95, v83
	v_mov_b32_e32 v94, v82
	v_mov_b32_e32 v97, v81
	v_mov_b32_e32 v96, v80
	v_mov_b32_e32 v91, v87
	v_mov_b32_e32 v90, v86
	v_mov_b32_e32 v93, v85
	v_mov_b32_e32 v92, v84
	s_cbranch_vccnz .LBB0_645
	v_max_f32_e32 v92, v81, v81
	v_max_f32_e32 v95, 0, v92
	v_max_f32_e32 v92, v86, v86
	v_max_f32_e32 v96, 0, v92
	v_max_f32_e32 v92, v82, v82
	v_max_f32_e32 v91, v80, v80
	v_max_f32_e32 v98, 0, v92
	v_max_f32_e32 v92, v87, v87
	v_max_f32_e32 v90, v84, v84
	v_max_f32_e32 v94, 0, v91
	v_max_f32_e32 v91, v85, v85
	v_max_f32_e32 v97, 0, v92
	v_max_f32_e32 v92, v83, v83
	v_max_f32_e32 v90, 0, v90
	v_max_f32_e32 v91, 0, v91
	v_max_f32_e32 v99, 0, v92
	v_pk_mul_f32 v[92:93], v[90:91], v[90:91]
	v_pk_mul_f32 v[90:91], v[96:97], v[96:97]
	v_pk_mul_f32 v[96:97], v[94:95], v[94:95]
	v_pk_mul_f32 v[94:95], v[98:99], v[98:99]

.LBB0_648:
	v_cvt_pk_bf16_f32 v80, v92, v93
	v_cvt_pk_bf16_f32 v81, v90, v91
	v_cvt_pk_bf16_f32 v82, v96, v97
	v_cvt_pk_bf16_f32 v83, v94, v95
	global_store_dwordx4 v[88:89], v[80:83], off offset:256
	s_mov_b64 s[22:23], -1
	s_and_b64 vcc, exec, s[4:5]
	v_add_u32_e32 v80, 0x80, v162
	v_ashrrev_i32_e32 v81, 31, v80
	v_lshlrev_b64 v[82:83], 6, v[80:81]
	v_lshl_add_u64 v[94:95], s[40:41], 0, v[82:83]
	global_load_dwordx4 v[214:217], v239, s[40:41] offset:1024
	global_load_dwordx4 v[218:221], v239, s[40:41] offset:1040
	global_load_dwordx4 v[222:225], v239, s[40:41] offset:1056
	global_load_dwordx4 v[226:229], v239, s[40:41] offset:1072
	s_waitcnt vmcnt(6) lgkmcnt(0)
	v_mov_b32_e32 v82, v230
	v_mov_b32_e32 v83, v231
	v_mov_b32_e32 v84, v232
	v_mov_b32_e32 v85, v233
	v_mov_b32_e32 v86, v234
	v_mov_b32_e32 v87, v235
	v_mov_b32_e32 v88, v236
	v_mov_b32_e32 v89, v237
	v_mov_b32_e32 v90, v206
	v_mov_b32_e32 v91, v207
	v_mov_b32_e32 v92, v208
	v_mov_b32_e32 v93, v209
	v_mov_b32_e32 v94, v210
	v_mov_b32_e32 v95, v211
	v_mov_b32_e32 v96, v212
	v_mov_b32_e32 v97, v213
	v_mov_b32_e32 v98, v83
	v_mov_b32_e32 v99, v84
	v_mov_b32_e32 v83, v85
	v_mov_b32_e32 v84, v87
	v_mov_b32_e32 v85, v88
	v_mov_b32_e32 v87, v89
	v_pk_add_f32 v[82:83], v[98:99], v[82:83]
	v_pk_add_f32 v[84:85], v[84:85], v[86:87]
	v_pk_add_f32 v[82:83], v[82:83], v[82:83] op_sel:[0,1] op_sel_hi:[1,0]
	v_pk_add_f32 v[84:85], v[84:85], v[84:85] op_sel:[0,1] op_sel_hi:[1,0]
	v_add_f32_e32 v86, v90, v91
	v_add_f32_e32 v88, v92, v93
	v_mov_b32_e32 v83, v94
	v_mov_b32_e32 v85, v95
	v_mov_b32_e32 v87, v96
	v_mov_b32_e32 v89, v97
	v_pk_add_f32 v[82:83], v[82:83], v[84:85]
	v_pk_add_f32 v[84:85], v[86:87], v[88:89]
	s_nop 0
	v_pk_add_f32 v[82:83], v[82:83], v[84:85]
	s_nop 0
	v_add_f32_e32 v82, v82, v83
	v_fmamk_f32 v82, v82, 0x3a800000, v183
	v_rsq_f32_e32 v82, v82
	s_nop 0
	v_mul_f32_e32 v82, s62, v82
	v_pk_fma_f32 v[78:79], v[78:79], v[82:83], v[38:39] op_sel_hi:[1,0,1]
	v_pk_fma_f32 v[76:77], v[76:77], v[82:83], v[36:37] op_sel_hi:[1,0,1]
	v_pk_fma_f32 v[74:75], v[74:75], v[82:83], v[34:35] op_sel_hi:[1,0,1]
	v_pk_fma_f32 v[72:73], v[72:73], v[82:83], v[32:33] op_sel_hi:[1,0,1]
	s_cbranch_vccnz .LBB0_652
	s_andn2_b64 vcc, exec, s[30:31]
	v_mov_b32_e32 v89, v75
	v_mov_b32_e32 v88, v74
	v_mov_b32_e32 v91, v73
	v_mov_b32_e32 v90, v72
	v_mov_b32_e32 v85, v79
	v_mov_b32_e32 v84, v78
	v_mov_b32_e32 v87, v77
	v_mov_b32_e32 v86, v76
	s_cbranch_vccnz .LBB0_651
	v_max_f32_e32 v83, v76, v76
	v_max_f32_e32 v84, 0, v83
	v_max_f32_e32 v83, v72, v72
	v_max_f32_e32 v88, 0, v83
	v_max_f32_e32 v83, v77, v77
	v_max_f32_e32 v85, 0, v83
	v_max_f32_e32 v83, v73, v73
	v_max_f32_e32 v89, 0, v83
	v_max_f32_e32 v83, v78, v78
	v_max_f32_e32 v90, 0, v83
	v_max_f32_e32 v83, v74, v74
	v_max_f32_e32 v92, 0, v83
	v_max_f32_e32 v83, v79, v79
	v_max_f32_e32 v91, 0, v83
	v_max_f32_e32 v83, v75, v75
	v_max_f32_e32 v93, 0, v83
	v_pk_mul_f32 v[86:87], v[84:85], v[84:85]
	v_pk_mul_f32 v[84:85], v[90:91], v[90:91]
	v_pk_mul_f32 v[90:91], v[88:89], v[88:89]
	v_pk_mul_f32 v[88:89], v[92:93], v[92:93]

.LBB0_654:
	v_mad_u64_u32 v[72:73], s[22:23], v80, s60, 0
	v_mov_b32_e32 v74, v73
	v_mad_u64_u32 v[74:75], s[22:23], v81, s60, v[74:75]
	v_mov_b32_e32 v73, v74
	v_lshl_add_u64 v[72:73], v[72:73], 1, s[36:37]
	v_lshl_add_u64 v[72:73], v[160:161], 1, v[72:73]
	v_cvt_pk_bf16_f32 v74, v86, v87
	v_cvt_pk_bf16_f32 v75, v84, v85
	v_cvt_pk_bf16_f32 v76, v90, v91
	v_cvt_pk_bf16_f32 v77, v88, v89
	v_mov_b32_e32 v83, v82
	global_store_dwordx4 v[72:73], v[74:77], off
	v_pk_fma_f32 v[68:69], v[68:69], v[82:83], v[28:29]
	v_pk_fma_f32 v[64:65], v[64:65], v[82:83], v[24:25]
	v_mov_b32_e32 v74, v82
	v_mov_b32_e32 v75, v82
	v_pk_fma_f32 v[70:71], v[70:71], v[74:75], v[30:31]
	v_pk_fma_f32 v[66:67], v[66:67], v[74:75], v[26:27]
	s_and_b64 vcc, exec, s[4:5]
	s_mov_b64 s[22:23], -1
	s_cbranch_vccnz .LBB0_658
	s_andn2_b64 vcc, exec, s[30:31]
	v_mov_b32_e32 v79, v67
	v_mov_b32_e32 v78, v66
	v_mov_b32_e32 v81, v65
	v_mov_b32_e32 v80, v64
	v_mov_b32_e32 v75, v71
	v_mov_b32_e32 v74, v70
	v_mov_b32_e32 v77, v69
	v_mov_b32_e32 v76, v68
	s_cbranch_vccnz .LBB0_657
	v_max_f32_e32 v76, v65, v65
	v_max_f32_e32 v79, 0, v76
	v_max_f32_e32 v76, v70, v70
	v_max_f32_e32 v80, 0, v76
	v_max_f32_e32 v76, v66, v66
	v_max_f32_e32 v75, v64, v64
	v_max_f32_e32 v82, 0, v76
	v_max_f32_e32 v76, v71, v71
	v_max_f32_e32 v74, v68, v68
	v_max_f32_e32 v78, 0, v75
	v_max_f32_e32 v75, v69, v69
	v_max_f32_e32 v81, 0, v76
	v_max_f32_e32 v76, v67, v67
	v_max_f32_e32 v74, 0, v74
	v_max_f32_e32 v75, 0, v75
	v_max_f32_e32 v83, 0, v76
	v_pk_mul_f32 v[76:77], v[74:75], v[74:75]
	v_pk_mul_f32 v[74:75], v[80:81], v[80:81]
	v_pk_mul_f32 v[80:81], v[78:79], v[78:79]
	v_pk_mul_f32 v[78:79], v[82:83], v[82:83]

.LBB0_660:
	v_cvt_pk_bf16_f32 v64, v76, v77
	v_cvt_pk_bf16_f32 v65, v74, v75
	v_cvt_pk_bf16_f32 v66, v80, v81
	v_cvt_pk_bf16_f32 v67, v78, v79
	global_store_dwordx4 v[72:73], v[64:67], off offset:256
	s_mov_b64 s[22:23], -1
	s_and_b64 vcc, exec, s[4:5]
	v_add_u32_e32 v64, 0x90, v162
	v_ashrrev_i32_e32 v65, 31, v64
	v_lshlrev_b64 v[66:67], 6, v[64:65]
	v_lshl_add_u64 v[78:79], s[40:41], 0, v[66:67]
	global_load_dwordx4 v[230:233], v239, s[40:41] offset:2048
	global_load_dwordx4 v[234:237], v239, s[40:41] offset:2064
	global_load_dwordx4 v[206:209], v239, s[40:41] offset:2080
	global_load_dwordx4 v[210:213], v239, s[40:41] offset:2096
	s_waitcnt vmcnt(6) lgkmcnt(0)
	v_mov_b32_e32 v66, v214
	v_mov_b32_e32 v67, v215
	v_mov_b32_e32 v68, v216
	v_mov_b32_e32 v69, v217
	v_mov_b32_e32 v70, v218
	v_mov_b32_e32 v71, v219
	v_mov_b32_e32 v72, v220
	v_mov_b32_e32 v73, v221
	v_mov_b32_e32 v74, v222
	v_mov_b32_e32 v75, v223
	v_mov_b32_e32 v76, v224
	v_mov_b32_e32 v77, v225
	v_mov_b32_e32 v78, v226
	v_mov_b32_e32 v79, v227
	v_mov_b32_e32 v80, v228
	v_mov_b32_e32 v81, v229
	v_mov_b32_e32 v82, v67
	v_mov_b32_e32 v83, v68
	v_mov_b32_e32 v67, v69
	v_mov_b32_e32 v68, v71
	v_mov_b32_e32 v69, v72
	v_mov_b32_e32 v71, v73
	v_pk_add_f32 v[66:67], v[82:83], v[66:67]
	v_pk_add_f32 v[68:69], v[68:69], v[70:71]
	v_pk_add_f32 v[66:67], v[66:67], v[66:67] op_sel:[0,1] op_sel_hi:[1,0]
	v_pk_add_f32 v[68:69], v[68:69], v[68:69] op_sel:[0,1] op_sel_hi:[1,0]
	v_add_f32_e32 v70, v74, v75
	v_add_f32_e32 v72, v76, v77
	v_mov_b32_e32 v67, v78
	v_mov_b32_e32 v69, v79
	v_mov_b32_e32 v71, v80
	v_mov_b32_e32 v73, v81
	v_pk_add_f32 v[66:67], v[66:67], v[68:69]
	v_pk_add_f32 v[68:69], v[70:71], v[72:73]
	s_nop 0
	v_pk_add_f32 v[66:67], v[66:67], v[68:69]
	s_nop 0
	v_add_f32_e32 v66, v66, v67
	v_fmamk_f32 v66, v66, 0x3a800000, v183
	v_rsq_f32_e32 v66, v66
	s_nop 0
	v_mul_f32_e32 v66, s62, v66
	v_pk_fma_f32 v[62:63], v[62:63], v[66:67], v[38:39] op_sel_hi:[1,0,1]
	v_pk_fma_f32 v[60:61], v[60:61], v[66:67], v[36:37] op_sel_hi:[1,0,1]
	v_pk_fma_f32 v[58:59], v[58:59], v[66:67], v[34:35] op_sel_hi:[1,0,1]
	v_pk_fma_f32 v[56:57], v[56:57], v[66:67], v[32:33] op_sel_hi:[1,0,1]
	s_cbranch_vccnz .LBB0_664
	s_andn2_b64 vcc, exec, s[30:31]
	v_mov_b32_e32 v73, v59
	v_mov_b32_e32 v72, v58
	v_mov_b32_e32 v75, v57
	v_mov_b32_e32 v74, v56
	v_mov_b32_e32 v69, v63
	v_mov_b32_e32 v68, v62
	v_mov_b32_e32 v71, v61
	v_mov_b32_e32 v70, v60
	s_cbranch_vccnz .LBB0_663
	v_max_f32_e32 v67, v60, v60
	v_max_f32_e32 v68, 0, v67
	v_max_f32_e32 v67, v56, v56
	v_max_f32_e32 v72, 0, v67
	v_max_f32_e32 v67, v61, v61
	v_max_f32_e32 v69, 0, v67
	v_max_f32_e32 v67, v57, v57
	v_max_f32_e32 v73, 0, v67
	v_max_f32_e32 v67, v62, v62
	v_max_f32_e32 v74, 0, v67
	v_max_f32_e32 v67, v58, v58
	v_max_f32_e32 v76, 0, v67
	v_max_f32_e32 v67, v63, v63
	v_max_f32_e32 v75, 0, v67
	v_max_f32_e32 v67, v59, v59
	v_max_f32_e32 v77, 0, v67
	v_pk_mul_f32 v[70:71], v[68:69], v[68:69]
	v_pk_mul_f32 v[68:69], v[74:75], v[74:75]
	v_pk_mul_f32 v[74:75], v[72:73], v[72:73]
	v_pk_mul_f32 v[72:73], v[76:77], v[76:77]

.LBB0_666:
	v_mad_u64_u32 v[56:57], s[22:23], v64, s60, 0
	v_mov_b32_e32 v58, v57
	v_mad_u64_u32 v[58:59], s[22:23], v65, s60, v[58:59]
	v_mov_b32_e32 v57, v58
	v_lshl_add_u64 v[56:57], v[56:57], 1, s[36:37]
	v_lshl_add_u64 v[56:57], v[160:161], 1, v[56:57]
	v_cvt_pk_bf16_f32 v58, v70, v71
	v_cvt_pk_bf16_f32 v59, v68, v69
	v_cvt_pk_bf16_f32 v60, v74, v75
	v_cvt_pk_bf16_f32 v61, v72, v73
	v_mov_b32_e32 v67, v66
	global_store_dwordx4 v[56:57], v[58:61], off
	v_pk_fma_f32 v[52:53], v[52:53], v[66:67], v[28:29]
	v_pk_fma_f32 v[48:49], v[48:49], v[66:67], v[24:25]
	v_mov_b32_e32 v58, v66
	v_mov_b32_e32 v59, v66
	v_pk_fma_f32 v[54:55], v[54:55], v[58:59], v[30:31]
	v_pk_fma_f32 v[50:51], v[50:51], v[58:59], v[26:27]
	s_and_b64 vcc, exec, s[4:5]
	s_mov_b64 s[22:23], -1
	s_cbranch_vccnz .LBB0_670
	s_andn2_b64 vcc, exec, s[30:31]
	v_mov_b32_e32 v63, v51
	v_mov_b32_e32 v62, v50
	v_mov_b32_e32 v65, v49
	v_mov_b32_e32 v64, v48
	v_mov_b32_e32 v59, v55
	v_mov_b32_e32 v58, v54
	v_mov_b32_e32 v61, v53
	v_mov_b32_e32 v60, v52
	s_cbranch_vccnz .LBB0_669
	v_max_f32_e32 v60, v49, v49
	v_max_f32_e32 v63, 0, v60
	v_max_f32_e32 v60, v54, v54
	v_max_f32_e32 v64, 0, v60
	v_max_f32_e32 v60, v50, v50
	v_max_f32_e32 v59, v48, v48
	v_max_f32_e32 v66, 0, v60
	v_max_f32_e32 v60, v55, v55
	v_max_f32_e32 v58, v52, v52
	v_max_f32_e32 v62, 0, v59
	v_max_f32_e32 v59, v53, v53
	v_max_f32_e32 v65, 0, v60
	v_max_f32_e32 v60, v51, v51
	v_max_f32_e32 v58, 0, v58
	v_max_f32_e32 v59, 0, v59
	v_max_f32_e32 v67, 0, v60
	v_pk_mul_f32 v[60:61], v[58:59], v[58:59]
	v_pk_mul_f32 v[58:59], v[64:65], v[64:65]
	v_pk_mul_f32 v[64:65], v[62:63], v[62:63]
	v_pk_mul_f32 v[62:63], v[66:67], v[66:67]

.LBB0_672:
	v_cvt_pk_bf16_f32 v48, v60, v61
	v_cvt_pk_bf16_f32 v49, v58, v59
	v_cvt_pk_bf16_f32 v50, v64, v65
	v_cvt_pk_bf16_f32 v51, v62, v63
	global_store_dwordx4 v[56:57], v[48:51], off offset:256
	s_mov_b64 s[22:23], -1
	s_and_b64 vcc, exec, s[4:5]
	v_add_u32_e32 v48, 0xa0, v162
	v_ashrrev_i32_e32 v49, 31, v48
	v_lshlrev_b64 v[50:51], 6, v[48:49]
	v_lshl_add_u64 v[62:63], s[40:41], 0, v[50:51]
	global_load_dwordx4 v[214:217], v239, s[40:41] offset:3072
	global_load_dwordx4 v[218:221], v239, s[40:41] offset:3088
	global_load_dwordx4 v[222:225], v239, s[40:41] offset:3104
	global_load_dwordx4 v[226:229], v239, s[40:41] offset:3120
	s_waitcnt vmcnt(6) lgkmcnt(0)
	v_mov_b32_e32 v50, v230
	v_mov_b32_e32 v51, v231
	v_mov_b32_e32 v52, v232
	v_mov_b32_e32 v53, v233
	v_mov_b32_e32 v54, v234
	v_mov_b32_e32 v55, v235
	v_mov_b32_e32 v56, v236
	v_mov_b32_e32 v57, v237
	v_mov_b32_e32 v58, v206
	v_mov_b32_e32 v59, v207
	v_mov_b32_e32 v60, v208
	v_mov_b32_e32 v61, v209
	v_mov_b32_e32 v62, v210
	v_mov_b32_e32 v63, v211
	v_mov_b32_e32 v64, v212
	v_mov_b32_e32 v65, v213
	v_mov_b32_e32 v66, v51
	v_mov_b32_e32 v67, v52
	v_mov_b32_e32 v51, v53
	v_mov_b32_e32 v52, v55
	v_mov_b32_e32 v53, v56
	v_mov_b32_e32 v55, v57
	v_pk_add_f32 v[50:51], v[66:67], v[50:51]
	v_pk_add_f32 v[52:53], v[52:53], v[54:55]
	v_pk_add_f32 v[50:51], v[50:51], v[50:51] op_sel:[0,1] op_sel_hi:[1,0]
	v_pk_add_f32 v[52:53], v[52:53], v[52:53] op_sel:[0,1] op_sel_hi:[1,0]
	v_add_f32_e32 v54, v58, v59
	v_add_f32_e32 v56, v60, v61
	v_mov_b32_e32 v51, v62
	v_mov_b32_e32 v53, v63
	v_mov_b32_e32 v55, v64
	v_mov_b32_e32 v57, v65
	v_pk_add_f32 v[50:51], v[50:51], v[52:53]
	v_pk_add_f32 v[52:53], v[54:55], v[56:57]
	s_nop 0
	v_pk_add_f32 v[50:51], v[50:51], v[52:53]
	s_nop 0
	v_add_f32_e32 v50, v50, v51
	v_fmamk_f32 v50, v50, 0x3a800000, v183
	v_rsq_f32_e32 v50, v50
	s_nop 0
	v_mul_f32_e32 v50, s62, v50
	v_pk_fma_f32 v[46:47], v[46:47], v[50:51], v[38:39] op_sel_hi:[1,0,1]
	v_pk_fma_f32 v[44:45], v[44:45], v[50:51], v[36:37] op_sel_hi:[1,0,1]
	v_pk_fma_f32 v[42:43], v[42:43], v[50:51], v[34:35] op_sel_hi:[1,0,1]
	v_pk_fma_f32 v[40:41], v[40:41], v[50:51], v[32:33] op_sel_hi:[1,0,1]
	s_cbranch_vccnz .LBB0_676
	s_andn2_b64 vcc, exec, s[30:31]
	v_mov_b32_e32 v57, v43
	v_mov_b32_e32 v56, v42
	v_mov_b32_e32 v59, v41
	v_mov_b32_e32 v58, v40
	v_mov_b32_e32 v53, v47
	v_mov_b32_e32 v52, v46
	v_mov_b32_e32 v55, v45
	v_mov_b32_e32 v54, v44
	s_cbranch_vccnz .LBB0_675
	v_max_f32_e32 v51, v44, v44
	v_max_f32_e32 v52, 0, v51
	v_max_f32_e32 v51, v40, v40
	v_max_f32_e32 v56, 0, v51
	v_max_f32_e32 v51, v45, v45
	v_max_f32_e32 v53, 0, v51
	v_max_f32_e32 v51, v41, v41
	v_max_f32_e32 v57, 0, v51
	v_max_f32_e32 v51, v46, v46
	v_max_f32_e32 v58, 0, v51
	v_max_f32_e32 v51, v42, v42
	v_max_f32_e32 v60, 0, v51
	v_max_f32_e32 v51, v47, v47
	v_max_f32_e32 v59, 0, v51
	v_max_f32_e32 v51, v43, v43
	v_max_f32_e32 v61, 0, v51
	v_pk_mul_f32 v[54:55], v[52:53], v[52:53]
	v_pk_mul_f32 v[52:53], v[58:59], v[58:59]
	v_pk_mul_f32 v[58:59], v[56:57], v[56:57]
	v_pk_mul_f32 v[56:57], v[60:61], v[60:61]

.LBB0_678:
	v_mad_u64_u32 v[40:41], s[22:23], v48, s60, 0
	v_mov_b32_e32 v42, v41
	v_mad_u64_u32 v[42:43], s[22:23], v49, s60, v[42:43]
	v_mov_b32_e32 v41, v42
	v_lshl_add_u64 v[40:41], v[40:41], 1, s[36:37]
	v_lshl_add_u64 v[40:41], v[160:161], 1, v[40:41]
	v_cvt_pk_bf16_f32 v42, v54, v55
	v_cvt_pk_bf16_f32 v43, v52, v53
	v_cvt_pk_bf16_f32 v44, v58, v59
	v_cvt_pk_bf16_f32 v45, v56, v57
	v_mov_b32_e32 v51, v50
	global_store_dwordx4 v[40:41], v[42:45], off
	v_pk_fma_f32 v[20:21], v[20:21], v[50:51], v[28:29]
	v_pk_fma_f32 v[16:17], v[16:17], v[50:51], v[24:25]
	v_mov_b32_e32 v42, v50
	v_mov_b32_e32 v43, v50
	v_pk_fma_f32 v[22:23], v[22:23], v[42:43], v[30:31]
	v_pk_fma_f32 v[18:19], v[18:19], v[42:43], v[26:27]
	s_and_b64 vcc, exec, s[4:5]
	s_mov_b64 s[22:23], -1
	s_cbranch_vccnz .LBB0_682
	s_andn2_b64 vcc, exec, s[30:31]
	v_mov_b32_e32 v47, v19
	v_mov_b32_e32 v46, v18
	v_mov_b32_e32 v49, v17
	v_mov_b32_e32 v48, v16
	v_mov_b32_e32 v43, v23
	v_mov_b32_e32 v42, v22
	v_mov_b32_e32 v45, v21
	v_mov_b32_e32 v44, v20
	s_cbranch_vccnz .LBB0_681
	v_max_f32_e32 v44, v17, v17
	v_max_f32_e32 v47, 0, v44
	v_max_f32_e32 v44, v22, v22
	v_max_f32_e32 v48, 0, v44
	v_max_f32_e32 v44, v18, v18
	v_max_f32_e32 v43, v16, v16
	v_max_f32_e32 v50, 0, v44
	v_max_f32_e32 v44, v23, v23
	v_max_f32_e32 v42, v20, v20
	v_max_f32_e32 v46, 0, v43
	v_max_f32_e32 v43, v21, v21
	v_max_f32_e32 v49, 0, v44
	v_max_f32_e32 v44, v19, v19
	v_max_f32_e32 v42, 0, v42
	v_max_f32_e32 v43, 0, v43
	v_max_f32_e32 v51, 0, v44
	v_pk_mul_f32 v[44:45], v[42:43], v[42:43]
	v_pk_mul_f32 v[42:43], v[48:49], v[48:49]
	v_pk_mul_f32 v[48:49], v[46:47], v[46:47]
	v_pk_mul_f32 v[46:47], v[50:51], v[50:51]

.LBB0_684:
	v_cvt_pk_bf16_f32 v16, v44, v45
	v_cvt_pk_bf16_f32 v17, v42, v43
	v_cvt_pk_bf16_f32 v18, v48, v49
	v_cvt_pk_bf16_f32 v19, v46, v47
	global_store_dwordx4 v[40:41], v[16:19], off offset:256
	s_mov_b64 s[22:23], -1
	s_and_b64 vcc, exec, s[4:5]
	v_add_u32_e32 v16, 0xb0, v162
	v_ashrrev_i32_e32 v17, 31, v16
	v_lshlrev_b64 v[18:19], 6, v[16:17]
	v_lshl_add_u64 v[22:23], s[40:41], 0, v[18:19]
	s_waitcnt vmcnt(2) lgkmcnt(0)
	v_mov_b32_e32 v18, v214
	v_mov_b32_e32 v19, v215
	v_mov_b32_e32 v20, v216
	v_mov_b32_e32 v21, v217
	v_mov_b32_e32 v40, v218
	v_mov_b32_e32 v41, v219
	v_mov_b32_e32 v42, v220
	v_mov_b32_e32 v43, v221
	v_mov_b32_e32 v44, v222
	v_mov_b32_e32 v45, v223
	v_mov_b32_e32 v46, v224
	v_mov_b32_e32 v47, v225
	v_mov_b32_e32 v48, v226
	v_mov_b32_e32 v49, v227
	v_mov_b32_e32 v50, v228
	v_mov_b32_e32 v51, v229
	v_mov_b32_e32 v22, v19
	v_mov_b32_e32 v23, v20
	v_mov_b32_e32 v19, v21
	v_mov_b32_e32 v20, v41
	v_mov_b32_e32 v21, v42
	v_mov_b32_e32 v41, v43
	v_pk_add_f32 v[18:19], v[22:23], v[18:19]
	v_pk_add_f32 v[20:21], v[20:21], v[40:41]
	v_pk_add_f32 v[18:19], v[18:19], v[18:19] op_sel:[0,1] op_sel_hi:[1,0]
	v_pk_add_f32 v[20:21], v[20:21], v[20:21] op_sel:[0,1] op_sel_hi:[1,0]
	v_add_f32_e32 v22, v44, v45
	v_add_f32_e32 v40, v46, v47
	v_mov_b32_e32 v19, v48
	v_mov_b32_e32 v21, v49
	v_mov_b32_e32 v23, v50
	v_mov_b32_e32 v41, v51
	v_pk_add_f32 v[18:19], v[18:19], v[20:21]
	v_pk_add_f32 v[20:21], v[22:23], v[40:41]
	s_nop 0
	v_pk_add_f32 v[18:19], v[18:19], v[20:21]
	s_nop 0
	v_add_f32_e32 v18, v18, v19
	v_fmamk_f32 v18, v18, 0x3a800000, v183
	v_rsq_f32_e32 v18, v18
	s_nop 0
	v_mul_f32_e32 v18, s62, v18
	v_pk_fma_f32 v[14:15], v[14:15], v[18:19], v[38:39] op_sel_hi:[1,0,1]
	v_pk_fma_f32 v[12:13], v[12:13], v[18:19], v[36:37] op_sel_hi:[1,0,1]
	v_pk_fma_f32 v[10:11], v[10:11], v[18:19], v[34:35] op_sel_hi:[1,0,1]
	v_pk_fma_f32 v[8:9], v[8:9], v[18:19], v[32:33] op_sel_hi:[1,0,1]
	s_cbranch_vccnz .LBB0_688
	s_andn2_b64 vcc, exec, s[30:31]
	v_mov_b32_e32 v33, v11
	v_mov_b32_e32 v32, v10
	v_mov_b32_e32 v35, v9
	v_mov_b32_e32 v34, v8
	v_mov_b32_e32 v21, v15
	v_mov_b32_e32 v20, v14
	v_mov_b32_e32 v23, v13
	v_mov_b32_e32 v22, v12
	s_cbranch_vccnz .LBB0_687
	v_max_f32_e32 v19, v12, v12
	v_max_f32_e32 v20, 0, v19
	v_max_f32_e32 v19, v8, v8
	v_max_f32_e32 v32, 0, v19
	v_max_f32_e32 v19, v13, v13
	v_max_f32_e32 v21, 0, v19
	v_max_f32_e32 v19, v9, v9
	v_max_f32_e32 v33, 0, v19
	v_max_f32_e32 v19, v14, v14
	v_max_f32_e32 v34, 0, v19
	v_max_f32_e32 v19, v10, v10
	v_max_f32_e32 v36, 0, v19
	v_max_f32_e32 v19, v15, v15
	v_max_f32_e32 v35, 0, v19
	v_max_f32_e32 v19, v11, v11
	v_max_f32_e32 v37, 0, v19
	v_pk_mul_f32 v[22:23], v[20:21], v[20:21]
	v_pk_mul_f32 v[20:21], v[34:35], v[34:35]
	v_pk_mul_f32 v[34:35], v[32:33], v[32:33]
	v_pk_mul_f32 v[32:33], v[36:37], v[36:37]

.LBB0_690:
	v_mad_u64_u32 v[8:9], s[22:23], v16, s60, 0
	v_mov_b32_e32 v10, v9
	v_mad_u64_u32 v[10:11], s[22:23], v17, s60, v[10:11]
	v_mov_b32_e32 v9, v10
	v_lshl_add_u64 v[8:9], v[8:9], 1, s[36:37]
	v_lshl_add_u64 v[8:9], v[160:161], 1, v[8:9]
	v_cvt_pk_bf16_f32 v10, v22, v23
	v_cvt_pk_bf16_f32 v11, v20, v21
	v_cvt_pk_bf16_f32 v12, v34, v35
	v_cvt_pk_bf16_f32 v13, v32, v33
	v_mov_b32_e32 v19, v18
	global_store_dwordx4 v[8:9], v[10:13], off
	v_pk_fma_f32 v[4:5], v[4:5], v[18:19], v[28:29]
	v_pk_fma_f32 v[0:1], v[0:1], v[18:19], v[24:25]
	v_mov_b32_e32 v10, v18
	v_mov_b32_e32 v11, v18
	v_pk_fma_f32 v[6:7], v[6:7], v[10:11], v[30:31]
	v_pk_fma_f32 v[2:3], v[2:3], v[10:11], v[26:27]
	s_and_b64 vcc, exec, s[4:5]
	s_mov_b64 s[4:5], -1
	s_cbranch_vccnz .LBB0_694
	s_andn2_b64 vcc, exec, s[30:31]
	v_mov_b32_e32 v15, v3
	v_mov_b32_e32 v14, v2
	v_mov_b32_e32 v17, v1
	v_mov_b32_e32 v16, v0
	v_mov_b32_e32 v11, v7
	v_mov_b32_e32 v10, v6
	v_mov_b32_e32 v13, v5
	v_mov_b32_e32 v12, v4
	s_cbranch_vccnz .LBB0_693
	v_max_f32_e32 v12, v1, v1
	v_max_f32_e32 v15, 0, v12
	v_max_f32_e32 v12, v6, v6
	v_max_f32_e32 v16, 0, v12
	v_max_f32_e32 v12, v2, v2
	v_max_f32_e32 v11, v0, v0
	v_max_f32_e32 v18, 0, v12
	v_max_f32_e32 v12, v7, v7
	v_max_f32_e32 v10, v4, v4
	v_max_f32_e32 v14, 0, v11
	v_max_f32_e32 v11, v5, v5
	v_max_f32_e32 v17, 0, v12
	v_max_f32_e32 v12, v3, v3
	v_max_f32_e32 v10, 0, v10
	v_max_f32_e32 v11, 0, v11
	v_max_f32_e32 v19, 0, v12
	v_pk_mul_f32 v[12:13], v[10:11], v[10:11]
	v_pk_mul_f32 v[10:11], v[16:17], v[16:17]
	v_pk_mul_f32 v[16:17], v[14:15], v[14:15]
	v_pk_mul_f32 v[14:15], v[18:19], v[18:19]

.LBB0_696:
	v_cvt_pk_bf16_f32 v0, v12, v13
	v_cvt_pk_bf16_f32 v1, v10, v11
	v_cvt_pk_bf16_f32 v2, v16, v17
	v_cvt_pk_bf16_f32 v3, v14, v15
	s_and_b64 vcc, exec, s[6:7]
	s_mov_b64 s[4:5], -1
	global_store_dwordx4 v[8:9], v[0:3], off offset:256
	s_cbranch_vccnz .LBB0_581
	s_andn2_b64 vcc, exec, s[12:13]
	s_cbranch_vccnz .LBB0_580
	s_barrier
	s_branch .LBB0_580
